# v40 + row reductions of the norm loops via permlane swaps and DPP (same pairing order) instead of ds_bpermute round trips
# speedup vs baseline: 1.0039x; 1.0039x over previous
; DI size_t kblk(int row, int col, int nrows) { return ((size_t)(col >> 5) * nrows + row) * 32 + (col & 31); }
; DI unsigned pk2(float a, float b) { hwf32x2 f = {a, b}; hwbf16x2 r = __builtin_convertvector(f, hwbf16x2); return __builtin_bit_cast(unsigned, r); }
; DI float wave_sum(float v) {
; #pragma unroll
;   for (int o = 32; o >= 1; o >>= 1) v += __shfl_xor(v, o);
;   return v;
; DI void ph_norm(const Params& p, int l, int bid, int nb) {
;     ...
;       for (int i = 0; i < 4; ++i) v[rr][i] = *(const float4*)(src + (i * 64 + lane) * 4);
;     }
; #pragma unroll
;     for (int rr = 0; rr < 2; ++rr) {
;       const int row = it * 8 + rr * 4 + w;
;       float ss = 0.f;
; #pragma unroll
;       for (int i = 0; i < 4; ++i) ss += v[rr][i].x * v[rr][i].x + v[rr][i].y * v[rr][i].y + v[rr][i].z * v[rr][i].z + v[rr][i].w * v[rr][i].w;
;       ss = wave_sum(ss);
;       const float rstd = rsqrtf(ss * (1.f / DM) + EPS);
; #pragma unroll
;       for (int i = 0; i < 4; ++i) {
;         const int j = (i * 64 + lane) * 4;
;         const float4 gg = *(const float4*)(g + j);
;         const float4 sh = *(const float4*)(mod[rr] + j);
;         const float4 sc = *(const float4*)(mod[rr] + 1024 + j);
;         uint2 o;
;         o.x = pk2(v[rr][i].x * rstd * gg.x * (1.f + sc.x) + sh.x, v[rr][i].y * rstd * gg.y * (1.f + sc.y) + sh.y);
;         o.y = pk2(v[rr][i].z * rstd * gg.z * (1.f + sc.z) + sh.z, v[rr][i].w * rstd * gg.w * (1.f + sc.w) + sh.w);
;         *(uint2*)(H + kblk(row, j, ROWS)) = o;
;       }
.LBB0_115:
	s_or_b64 exec, exec, s[8:9]
	v_lshlrev_b64 v[8:9], v16, v[8:9]
	v_lshl_add_u64 v[8:9], v[18:19], 0, v[8:9]
	v_lshlrev_b64 v[10:11], 12, v[10:11]
	v_lshl_add_u64 v[8:9], v[8:9], 0, v[10:11]
	v_lshl_add_u64 v[8:9], v[8:9], 0, v[46:47]
	global_load_dwordx4 v[28:31], v[8:9], off
	global_load_dwordx4 v[20:23], v[8:9], off offset:1024
	global_load_dwordx4 v[16:19], v[8:9], off offset:2048
	s_nop 0
	global_load_dwordx4 v[8:11], v[8:9], off offset:3072
	v_add_u32_e32 v45, s2, v58
	s_waitcnt vmcnt(0) lgkmcnt(0)
	v_mov_b32_e32 v70, v25
	v_mov_b32_e32 v71, v13
	v_mov_b32_e32 v58, v24
	v_mov_b32_e32 v59, v12
	v_mov_b32_e32 v78, v5
	v_mov_b32_e32 v79, v1
	v_mul_hi_i32_i24_e32 v85, 0x3000, v45
	v_mul_i32_i24_e32 v84, 0x3000, v45
	v_pk_mul_f32 v[70:71], v[70:71], v[70:71]
	v_mov_b32_e32 v72, v26
	v_mov_b32_e32 v73, v14
	v_mov_b32_e32 v76, v4
	v_mov_b32_e32 v77, v0
	v_pk_mul_f32 v[78:79], v[78:79], v[78:79]
	v_lshl_add_u64 v[84:85], s[0:1], 0, v[84:85]
	v_pk_fma_f32 v[58:59], v[58:59], v[58:59], v[70:71]
	s_mov_b64 s[12:13], 0x1000
	v_mov_b32_e32 v74, v27
	v_mov_b32_e32 v75, v15
	v_mov_b32_e32 v80, v6
	v_mov_b32_e32 v81, v2
	v_pk_fma_f32 v[70:71], v[76:77], v[76:77], v[78:79]
	v_pk_fma_f32 v[58:59], v[72:73], v[72:73], v[58:59]
	v_lshl_add_u64 v[78:79], v[84:85], 0, s[12:13]
	v_mov_b32_e32 v82, v7
	v_mov_b32_e32 v83, v3
	v_pk_fma_f32 v[70:71], v[80:81], v[80:81], v[70:71]
	v_lshl_add_u64 v[80:81], v[84:85], 0, v[46:47]
	v_pk_fma_f32 v[58:59], v[74:75], v[74:75], v[58:59]
	v_lshl_add_u64 v[74:75], v[78:79], 0, v[46:47]
	v_mov_b64_e32 v[66:67], v[104:105]
	v_mov_b64_e32 v[68:69], v[106:107]
	v_pk_fma_f32 v[82:83], v[82:83], v[82:83], v[70:71]
	global_load_dwordx4 v[70:73], v[80:81], off
	global_load_dwordx4 v[120:123], v[80:81], off offset:1024
	global_load_dwordx4 v[124:127], v[80:81], off offset:2048
	global_load_dwordx4 v[128:131], v[80:81], off offset:3072
	s_nop 0
	global_load_dwordx4 v[132:135], v[74:75], off offset:1024
	global_load_dwordx4 v[136:139], v[74:75], off offset:2048
	global_load_dwordx4 v[140:143], v[74:75], off offset:3072
	global_load_dwordx4 v[74:77], v[74:75], off
	v_mov_b32_e32 v85, v58
	v_mov_b32_e32 v87, v82
	s_mov_b32 s8, 0x3a800000
	v_ashrrev_i32_e32 v45, 31, v44
	s_add_i32 s10, s10, s54
	s_mov_b32 s38, 0x800000
	s_cmpk_lt_i32 s10, 0x900
	v_mov_b32_e32 v94, v29
	v_mov_b32_e32 v95, v21
	v_mov_b32_e32 v92, v28
	v_mov_b32_e32 v93, v20
	v_mov_b32_e32 v102, v17
	v_mov_b32_e32 v103, v9
	v_pk_mul_f32 v[94:95], v[94:95], v[94:95]
	v_mov_b32_e32 v88, v30
	v_mov_b32_e32 v89, v22
	v_mov_b32_e32 v100, v16
	v_mov_b32_e32 v101, v8
	v_pk_mul_f32 v[102:103], v[102:103], v[102:103]
	v_pk_fma_f32 v[92:93], v[92:93], v[92:93], v[94:95]
	v_mov_b32_e32 v90, v31
	v_mov_b32_e32 v91, v23
	v_mov_b32_e32 v96, v18
	v_mov_b32_e32 v97, v10
	v_pk_fma_f32 v[94:95], v[100:101], v[100:101], v[102:103]
	v_pk_fma_f32 v[88:89], v[88:89], v[88:89], v[92:93]
	v_mov_b32_e32 v98, v19
	v_mov_b32_e32 v99, v11
	v_pk_fma_f32 v[92:93], v[96:97], v[96:97], v[94:95]
	v_pk_fma_f32 v[88:89], v[90:91], v[90:91], v[88:89]
	v_pk_fma_f32 v[90:91], v[98:99], v[98:99], v[92:93]
	v_mov_b32_e32 v84, v88
	v_mov_b32_e32 v58, v89
	v_mov_b32_e32 v86, v90
	v_pk_add_f32 v[58:59], v[84:85], v[58:59]
	v_mov_b32_e32 v82, v91
	v_pk_add_f32 v[58:59], v[58:59], v[86:87]
	v_lshl_add_u64 v[84:85], v[44:45], 0, v[36:37]
	v_pk_add_f32 v[58:59], v[58:59], v[82:83]
	v_mov_b32_e32 v82, v58
	v_mov_b32_e32 v83, v59
	v_lshlrev_b64 v[84:85], 6, v[84:85]
	v_lshl_add_u64 v[84:85], v[32:33], 0, v[84:85]
	v_permlane32_swap_b32_e32 v82, v58
	v_permlane32_swap_b32_e32 v83, v59
	v_pk_add_f32 v[58:59], v[58:59], v[82:83]
	v_mov_b32_e32 v82, v58
	v_mov_b32_e32 v83, v59
	s_nop 1
	v_permlane16_swap_b32_e32 v82, v58
	v_permlane16_swap_b32_e32 v83, v59
	v_pk_add_f32 v[58:59], v[58:59], v[82:83]
	s_nop 1
	v_add_f32_dpp v58, v58, v58 row_ror:8 row_mask:0xf bank_mask:0xf
	v_add_f32_dpp v59, v59, v59 row_ror:8 row_mask:0xf bank_mask:0xf
	s_nop 0
	v_add_f32_dpp v82, v58, v58 row_shl:4 row_mask:0xf bank_mask:0x5
	v_add_f32_dpp v83, v59, v59 row_shl:4 row_mask:0xf bank_mask:0x5
	v_add_f32_dpp v82, v58, v58 row_shr:4 row_mask:0xf bank_mask:0xa
	v_add_f32_dpp v83, v59, v59 row_shr:4 row_mask:0xf bank_mask:0xa
	s_nop 0
	v_add_f32_dpp v58, v82, v82 quad_perm:[2,3,0,1] row_mask:0xf bank_mask:0xf
	v_add_f32_dpp v59, v83, v83 quad_perm:[2,3,0,1] row_mask:0xf bank_mask:0xf
	s_nop 0
	v_add_f32_dpp v58, v58, v58 quad_perm:[1,0,3,2] row_mask:0xf bank_mask:0xf
	v_add_f32_dpp v59, v59, v59 quad_perm:[1,0,3,2] row_mask:0xf bank_mask:0xf
	s_waitcnt vmcnt(0)
	v_pk_add_f32 v[74:75], v[74:75], 1.0 op_sel_hi:[1,0]
	v_pk_add_f32 v[76:77], v[76:77], 1.0 op_sel_hi:[1,0]
	s_nop 0
	v_pk_fma_f32 v[58:59], v[58:59], s[8:9], v[162:163] op_sel_hi:[1,0,0]
	s_mov_b32 s8, 0x800000
	v_mul_f32_e32 v55, 0x4b800000, v59
	v_cmp_gt_f32_e32 vcc, s8, v59
	v_lshl_add_u64 v[82:83], v[78:79], 0, v[48:49]
	s_nop 0
	v_cndmask_b32_e32 v55, v59, v55, vcc
	v_rsq_f32_e32 v55, v55
	s_nop 0
	v_mul_f32_e32 v57, 0x45800000, v55
	v_cndmask_b32_e32 v86, v55, v57, vcc
	v_pk_mul_f32 v[24:25], v[24:25], v[86:87] op_sel_hi:[1,0]
	v_pk_mul_f32 v[26:27], v[26:27], v[86:87] op_sel_hi:[1,0]
	v_pk_mul_f32 v[24:25], v[66:67], v[24:25]
	v_pk_mul_f32 v[26:27], v[68:69], v[26:27]
	v_pk_fma_f32 v[24:25], v[74:75], v[24:25], v[70:71]
	v_pk_fma_f32 v[26:27], v[26:27], v[76:77], v[72:73]
	v_cvt_pk_bf16_f32 v24, v24, v25
	v_cvt_pk_bf16_f32 v25, v26, v27
	global_store_dwordx2 v[84:85], v[24:25], off
	v_mov_b64_e32 v[24:25], v[108:109]
	v_mov_b64_e32 v[26:27], v[110:111]
	s_nop 0
	v_mov_b64_e32 v[66:67], v[132:133]
	v_mov_b64_e32 v[68:69], v[134:135]
	v_mov_b64_e32 v[70:71], v[120:121]
	v_mov_b64_e32 v[72:73], v[122:123]
	v_pk_mul_f32 v[12:13], v[12:13], v[86:87] op_sel_hi:[1,0]
	v_pk_mul_f32 v[14:15], v[14:15], v[86:87] op_sel_hi:[1,0]
	v_lshl_add_u64 v[74:75], v[44:45], 0, v[38:39]
	v_lshlrev_b64 v[74:75], 6, v[74:75]
	v_lshl_add_u64 v[74:75], v[32:33], 0, v[74:75]
	v_lshl_add_u64 v[76:77], v[78:79], 0, v[50:51]
	v_pk_mul_f32 v[4:5], v[4:5], v[86:87] op_sel_hi:[1,0]
	v_pk_mul_f32 v[6:7], v[6:7], v[86:87] op_sel_hi:[1,0]
	v_pk_mul_f32 v[0:1], v[0:1], v[86:87] op_sel_hi:[1,0]
	v_pk_mul_f32 v[2:3], v[2:3], v[86:87] op_sel_hi:[1,0]
	v_add_u32_e32 v55, s2, v56
	v_mul_hi_i32_i24_e32 v57, 0x3000, v55
	v_mul_i32_i24_e32 v56, 0x3000, v55
	v_lshl_add_u64 v[56:57], s[0:1], 0, v[56:57]
	v_cmp_gt_f32_e32 vcc, s8, v58
	v_ashrrev_i32_e32 v55, 31, v54
	v_readlane_b32 s8, v254, 11
	v_pk_mul_f32 v[12:13], v[12:13], v[24:25]
	s_waitcnt lgkmcnt(0)
; DI size_t kblk(int row, int col, int nrows) { return ((size_t)(col >> 5) * nrows + row) * 32 + (col & 31); }
; DI unsigned pk2(float a, float b) { hwf32x2 f = {a, b}; hwbf16x2 r = __builtin_convertvector(f, hwbf16x2); return __builtin_bit_cast(unsigned, r); }
; DI void ph_norm(const Params& p, int l, int bid, int nb) {
;     ...
; #pragma unroll
;       for (int i = 0; i < 4; ++i) {
;         const int j = (i * 64 + lane) * 4;
;         const float4 gg = *(const float4*)(g + j);
;         const float4 sh = *(const float4*)(mod[rr] + j);
;         const float4 sc = *(const float4*)(mod[rr] + 1024 + j);
;         uint2 o;
;         o.x = pk2(v[rr][i].x * rstd * gg.x * (1.f + sc.x) + sh.x, v[rr][i].y * rstd * gg.y * (1.f + sc.y) + sh.y);
;         o.y = pk2(v[rr][i].z * rstd * gg.z * (1.f + sc.z) + sh.z, v[rr][i].w * rstd * gg.w * (1.f + sc.w) + sh.w);
;         *(uint2*)(H + kblk(row, j, ROWS)) = o;
	v_pk_add_f32 v[24:25], v[66:67], 1.0 op_sel_hi:[1,0]
	v_pk_mul_f32 v[14:15], v[14:15], v[26:27]
	v_pk_add_f32 v[26:27], v[68:69], 1.0 op_sel_hi:[1,0]
	v_pk_fma_f32 v[12:13], v[12:13], v[24:25], v[70:71]
	v_pk_fma_f32 v[14:15], v[14:15], v[26:27], v[72:73]
	v_cvt_pk_bf16_f32 v12, v12, v13
	v_cvt_pk_bf16_f32 v13, v14, v15
	global_store_dwordx2 v[74:75], v[12:13], off
	v_mov_b64_e32 v[12:13], v[112:113]
	v_mov_b64_e32 v[14:15], v[114:115]
	s_nop 0
	v_mov_b64_e32 v[24:25], v[136:137]
	v_mov_b64_e32 v[26:27], v[138:139]
	v_mov_b64_e32 v[66:67], v[124:125]
	v_mov_b64_e32 v[68:69], v[126:127]
	v_lshl_add_u64 v[70:71], v[44:45], 0, v[40:41]
	v_lshlrev_b64 v[70:71], 6, v[70:71]
	v_lshl_add_u64 v[70:71], v[32:33], 0, v[70:71]
	v_lshl_add_u64 v[72:73], v[78:79], 0, v[52:53]
	v_pk_mul_f32 v[4:5], v[4:5], v[12:13]
	s_waitcnt lgkmcnt(0)
	v_pk_add_f32 v[12:13], v[24:25], 1.0 op_sel_hi:[1,0]
	v_pk_mul_f32 v[6:7], v[6:7], v[14:15]
	v_pk_add_f32 v[14:15], v[26:27], 1.0 op_sel_hi:[1,0]
	v_pk_fma_f32 v[4:5], v[4:5], v[12:13], v[66:67]
	v_pk_fma_f32 v[6:7], v[6:7], v[14:15], v[68:69]
	v_cvt_pk_bf16_f32 v4, v4, v5
	v_cvt_pk_bf16_f32 v5, v6, v7
	global_store_dwordx2 v[70:71], v[4:5], off
	v_mov_b64_e32 v[4:5], v[116:117]
	v_mov_b64_e32 v[6:7], v[118:119]
	s_nop 0
	v_mov_b64_e32 v[12:13], v[140:141]
	v_mov_b64_e32 v[14:15], v[142:143]
	v_mov_b64_e32 v[24:25], v[128:129]
	v_mov_b64_e32 v[26:27], v[130:131]
	v_lshl_add_u64 v[66:67], v[44:45], 0, v[42:43]
	v_lshlrev_b64 v[66:67], 6, v[66:67]
	v_lshl_add_u64 v[66:67], v[32:33], 0, v[66:67]
	v_lshl_add_u64 v[68:69], v[56:57], 0, s[12:13]
	v_lshl_add_u64 v[70:71], v[68:69], 0, v[46:47]
	v_mul_f32_e32 v45, 0x4b800000, v58
	v_cndmask_b32_e32 v45, v58, v45, vcc
	v_rsq_f32_e32 v45, v45
	v_add_u32_e32 v44, s8, v44
	v_mul_f32_e32 v58, 0x45800000, v45
	v_cndmask_b32_e32 v58, v45, v58, vcc
	v_pk_mul_f32 v[28:29], v[28:29], v[58:59] op_sel_hi:[1,0]
	v_pk_mul_f32 v[30:31], v[30:31], v[58:59] op_sel_hi:[1,0]
	v_pk_mul_f32 v[20:21], v[20:21], v[58:59] op_sel_hi:[1,0]
	v_pk_mul_f32 v[22:23], v[22:23], v[58:59] op_sel_hi:[1,0]
	v_pk_mul_f32 v[16:17], v[16:17], v[58:59] op_sel_hi:[1,0]
	v_pk_mul_f32 v[18:19], v[18:19], v[58:59] op_sel_hi:[1,0]
	v_pk_mul_f32 v[8:9], v[8:9], v[58:59] op_sel_hi:[1,0]
	v_pk_mul_f32 v[10:11], v[10:11], v[58:59] op_sel_hi:[1,0]
	v_pk_mul_f32 v[0:1], v[0:1], v[4:5]
	s_waitcnt lgkmcnt(0)
	v_pk_add_f32 v[4:5], v[12:13], 1.0 op_sel_hi:[1,0]
	v_pk_mul_f32 v[2:3], v[2:3], v[6:7]
	v_pk_add_f32 v[6:7], v[14:15], 1.0 op_sel_hi:[1,0]
	v_pk_fma_f32 v[0:1], v[0:1], v[4:5], v[24:25]
	v_pk_fma_f32 v[2:3], v[2:3], v[6:7], v[26:27]
	v_cvt_pk_bf16_f32 v0, v0, v1
	v_cvt_pk_bf16_f32 v1, v2, v3
	global_store_dwordx2 v[66:67], v[0:1], off
	v_mov_b64_e32 v[0:1], v[104:105]
	v_mov_b64_e32 v[2:3], v[106:107]
	s_nop 0
	global_load_dwordx4 v[4:7], v[70:71], off
	global_load_dwordx4 v[144:147], v[70:71], off offset:1024
	global_load_dwordx4 v[148:151], v[70:71], off offset:2048
	global_load_dwordx4 v[152:155], v[70:71], off offset:3072
	v_lshl_add_u64 v[24:25], v[56:57], 0, v[46:47]
	global_load_dwordx4 v[12:15], v[24:25], off
	global_load_dwordx4 v[156:159], v[24:25], off offset:1024
	global_load_dwordx4 v[196:199], v[24:25], off offset:2048
	global_load_dwordx4 v[200:203], v[24:25], off offset:3072
	v_lshl_add_u64 v[26:27], v[54:55], 0, v[36:37]
	v_lshlrev_b64 v[26:27], 6, v[26:27]
	v_lshl_add_u64 v[26:27], v[32:33], 0, v[26:27]
	v_lshl_add_u64 v[56:57], v[68:69], 0, v[48:49]
	s_waitcnt vmcnt(0)
	v_pk_mul_f32 v[0:1], v[0:1], v[28:29]
	s_waitcnt lgkmcnt(0)
	v_pk_add_f32 v[4:5], v[4:5], 1.0 op_sel_hi:[1,0]
	v_pk_mul_f32 v[2:3], v[2:3], v[30:31]
	v_pk_add_f32 v[6:7], v[6:7], 1.0 op_sel_hi:[1,0]
	v_pk_fma_f32 v[0:1], v[4:5], v[0:1], v[12:13]
	v_pk_fma_f32 v[2:3], v[2:3], v[6:7], v[14:15]
	v_cvt_pk_bf16_f32 v0, v0, v1
	v_cvt_pk_bf16_f32 v1, v2, v3
	global_store_dwordx2 v[26:27], v[0:1], off
	v_mov_b64_e32 v[0:1], v[108:109]
	v_mov_b64_e32 v[2:3], v[110:111]
	s_nop 0
	v_mov_b64_e32 v[4:5], v[144:145]
	v_mov_b64_e32 v[6:7], v[146:147]
	v_mov_b64_e32 v[12:13], v[156:157]
	v_mov_b64_e32 v[14:15], v[158:159]
	v_lshl_add_u64 v[26:27], v[54:55], 0, v[38:39]
	v_lshlrev_b64 v[26:27], 6, v[26:27]
	v_lshl_add_u64 v[26:27], v[32:33], 0, v[26:27]
	v_lshl_add_u64 v[28:29], v[68:69], 0, v[50:51]
	v_pk_mul_f32 v[0:1], v[20:21], v[0:1]
	s_waitcnt lgkmcnt(0)
	v_pk_add_f32 v[4:5], v[4:5], 1.0 op_sel_hi:[1,0]
	v_pk_mul_f32 v[2:3], v[22:23], v[2:3]
	v_pk_add_f32 v[6:7], v[6:7], 1.0 op_sel_hi:[1,0]
	v_pk_fma_f32 v[0:1], v[0:1], v[4:5], v[12:13]
	v_pk_fma_f32 v[2:3], v[2:3], v[6:7], v[14:15]
	v_cvt_pk_bf16_f32 v0, v0, v1
	v_cvt_pk_bf16_f32 v1, v2, v3
	global_store_dwordx2 v[26:27], v[0:1], off
	v_mov_b64_e32 v[0:1], v[112:113]
	v_mov_b64_e32 v[2:3], v[114:115]
	s_nop 0
	v_mov_b64_e32 v[4:5], v[148:149]
	v_mov_b64_e32 v[6:7], v[150:151]
	v_mov_b64_e32 v[12:13], v[196:197]
	v_mov_b64_e32 v[14:15], v[198:199]
	v_lshl_add_u64 v[20:21], v[54:55], 0, v[40:41]
	v_lshlrev_b64 v[20:21], 6, v[20:21]
	v_lshl_add_u64 v[20:21], v[32:33], 0, v[20:21]
	v_lshl_add_u64 v[22:23], v[68:69], 0, v[52:53]
	v_pk_mul_f32 v[0:1], v[16:17], v[0:1]
	s_waitcnt lgkmcnt(0)
	v_pk_add_f32 v[4:5], v[4:5], 1.0 op_sel_hi:[1,0]
	v_pk_mul_f32 v[2:3], v[18:19], v[2:3]
	v_pk_add_f32 v[6:7], v[6:7], 1.0 op_sel_hi:[1,0]
	v_pk_fma_f32 v[0:1], v[0:1], v[4:5], v[12:13]
	v_pk_fma_f32 v[2:3], v[2:3], v[6:7], v[14:15]
	v_cvt_pk_bf16_f32 v0, v0, v1
	v_cvt_pk_bf16_f32 v1, v2, v3
	global_store_dwordx2 v[20:21], v[0:1], off
	v_mov_b64_e32 v[0:1], v[116:117]
	v_mov_b64_e32 v[2:3], v[118:119]
	s_nop 0
	v_mov_b64_e32 v[4:5], v[152:153]
	v_mov_b64_e32 v[6:7], v[154:155]
	v_mov_b64_e32 v[12:13], v[200:201]
	v_mov_b64_e32 v[14:15], v[202:203]
	v_lshl_add_u64 v[16:17], v[54:55], 0, v[42:43]
	v_lshlrev_b64 v[16:17], 6, v[16:17]
	v_lshl_add_u64 v[16:17], v[32:33], 0, v[16:17]
	v_pk_mul_f32 v[0:1], v[8:9], v[0:1]
	s_waitcnt lgkmcnt(0)
	v_pk_add_f32 v[4:5], v[4:5], 1.0 op_sel_hi:[1,0]
	v_pk_mul_f32 v[2:3], v[10:11], v[2:3]
	v_pk_add_f32 v[6:7], v[6:7], 1.0 op_sel_hi:[1,0]
	v_pk_fma_f32 v[0:1], v[0:1], v[4:5], v[12:13]
	v_pk_fma_f32 v[2:3], v[2:3], v[6:7], v[14:15]
	v_cvt_pk_bf16_f32 v0, v0, v1
	v_cvt_pk_bf16_f32 v1, v2, v3
	global_store_dwordx2 v[16:17], v[0:1], off
	s_cbranch_scc0 .LBB0_124
